# GLA final pass output stage: LDS fragment reads batched ahead of each 8-MFMA chain
# baseline (speedup 1.0000x reference)
.LBB0_256:
	s_or_b64 exec, exec, s[8:9]
	s_lshl_b32 s8, s28, 4
	ds_write_b16 v49, v44 offset:528
	v_or_b32_e32 v44, s8, v123
	s_movk_i32 s7, 0x90
	v_mul_lo_u32 v44, v44, s7
	v_add_u32_e32 v86, 0, v3
	v_add3_u32 v44, s92, v44, v3
	v_lshlrev_b32_e32 v52, 4, v48
	v_mad_u32_u24 v48, v123, s7, v86
	s_waitcnt lgkmcnt(0)
	s_barrier
	s_add_i32 s6, 0, 0x10c00
	v_cmp_gt_u32_e32 vcc, 16, v124
	ds_read_b128 v[78:81], v44
	ds_read_b128 v[56:59], v44 offset:64
	v_add_u32_e32 v173, s6, v3
	v_mad_u32_u24 v180, v123, s7, v217
	v_mad_u32_u24 v181, v123, s7, v218
	v_mad_u32_u24 v182, v123, s7, v219
	v_mul_u32_u24_e32 v243, 0x48, v123
	v_add_u32_e32 v174, v173, v180
	v_add_u32_e32 v175, v173, v181
	v_add_u32_e32 v242, v173, v182
	v_mad_u32_u24 v173, v123, s7, v173
	v_lshlrev_b32_e32 v243, 1, v243
	v_add_u32_e32 v180, v86, v180
	v_add_u32_e32 v181, v86, v181
	v_add_u32_e32 v182, v86, v182
	v_add3_u32 v243, 0, v52, v243
	ds_read_b128 v[222:225], v48 offset:59392
	ds_read_b128 v[226:229], v48 offset:59456
	ds_read_b128 v[230:233], v173
	ds_read_b128 v[234:237], v173 offset:64
	ds_read_b128 v[238:241], v243 offset:22528
	ds_read_b128 v[196:199], v243 offset:22592
	ds_read_b128 v[200:203], v243 offset:31744
	ds_read_b128 v[176:179], v243 offset:31808
	s_waitcnt lgkmcnt(7)
	v_mfma_f32_16x16x32_bf16 v[52:55], v[78:81], v[222:225], 0
	s_waitcnt lgkmcnt(6)
	v_mfma_f32_16x16x32_bf16 v[52:55], v[56:59], v[226:229], v[52:55]
	s_waitcnt lgkmcnt(5)
	v_mfma_f32_16x16x32_bf16 v[52:55], v[78:81], v[230:233], v[52:55]
	s_waitcnt lgkmcnt(4)
	v_mfma_f32_16x16x32_bf16 v[52:55], v[56:59], v[234:237], v[52:55]
	s_waitcnt lgkmcnt(3)
	v_mfma_f32_16x16x32_bf16 v[52:55], v[8:11], v[238:241], v[52:55]
	s_waitcnt lgkmcnt(2)
	v_mfma_f32_16x16x32_bf16 v[52:55], v[12:15], v[196:199], v[52:55]
	s_waitcnt lgkmcnt(1)
	v_mfma_f32_16x16x32_bf16 v[52:55], v[16:19], v[200:203], v[52:55]
	s_waitcnt lgkmcnt(0)
	v_mfma_f32_16x16x32_bf16 v[52:55], v[20:23], v[176:179], v[52:55]
	ds_read_b128 v[222:225], v180 offset:59392
	ds_read_b128 v[226:229], v180 offset:59456
	ds_read_b128 v[230:233], v174
	ds_read_b128 v[234:237], v174 offset:64
	ds_read_b128 v[238:241], v243 offset:24832
	ds_read_b128 v[196:199], v243 offset:24896
	ds_read_b128 v[200:203], v243 offset:34048
	ds_read_b128 v[176:179], v243 offset:34112
	s_waitcnt lgkmcnt(7)
	v_mfma_f32_16x16x32_bf16 v[48:51], v[78:81], v[222:225], 0
	s_waitcnt lgkmcnt(6)
	v_mfma_f32_16x16x32_bf16 v[48:51], v[56:59], v[226:229], v[48:51]
	s_waitcnt lgkmcnt(5)
	v_mfma_f32_16x16x32_bf16 v[48:51], v[78:81], v[230:233], v[48:51]
	s_waitcnt lgkmcnt(4)
	v_mfma_f32_16x16x32_bf16 v[48:51], v[56:59], v[234:237], v[48:51]
	s_waitcnt lgkmcnt(3)
	v_mfma_f32_16x16x32_bf16 v[48:51], v[8:11], v[238:241], v[48:51]
	s_waitcnt lgkmcnt(2)
	v_mfma_f32_16x16x32_bf16 v[48:51], v[12:15], v[196:199], v[48:51]
	s_waitcnt lgkmcnt(1)
	v_mfma_f32_16x16x32_bf16 v[48:51], v[16:19], v[200:203], v[48:51]
	s_waitcnt lgkmcnt(0)
	v_mfma_f32_16x16x32_bf16 v[48:51], v[20:23], v[176:179], v[48:51]
	ds_read_b128 v[222:225], v181 offset:59392
	ds_read_b128 v[226:229], v181 offset:59456
	ds_read_b128 v[230:233], v175
	ds_read_b128 v[234:237], v175 offset:64
	ds_read_b128 v[238:241], v243 offset:27136
	ds_read_b128 v[196:199], v243 offset:27200
	ds_read_b128 v[200:203], v243 offset:36352
	ds_read_b128 v[176:179], v243 offset:36416
	s_waitcnt lgkmcnt(7)
	v_mfma_f32_16x16x32_bf16 v[44:47], v[78:81], v[222:225], 0
	s_waitcnt lgkmcnt(6)
	v_mfma_f32_16x16x32_bf16 v[44:47], v[56:59], v[226:229], v[44:47]
	s_waitcnt lgkmcnt(5)
	v_mfma_f32_16x16x32_bf16 v[44:47], v[78:81], v[230:233], v[44:47]
	s_waitcnt lgkmcnt(4)
	v_mfma_f32_16x16x32_bf16 v[44:47], v[56:59], v[234:237], v[44:47]
	s_waitcnt lgkmcnt(3)
	v_mfma_f32_16x16x32_bf16 v[44:47], v[8:11], v[238:241], v[44:47]
	s_waitcnt lgkmcnt(2)
	v_mfma_f32_16x16x32_bf16 v[44:47], v[12:15], v[196:199], v[44:47]
	s_waitcnt lgkmcnt(1)
	v_mfma_f32_16x16x32_bf16 v[44:47], v[16:19], v[200:203], v[44:47]
	s_waitcnt lgkmcnt(0)
	v_mfma_f32_16x16x32_bf16 v[44:47], v[20:23], v[176:179], v[44:47]
	ds_read_b128 v[222:225], v182 offset:59392
	ds_read_b128 v[226:229], v182 offset:59456
	ds_read_b128 v[230:233], v242
	ds_read_b128 v[234:237], v242 offset:64
	ds_read_b128 v[238:241], v243 offset:29440
	ds_read_b128 v[196:199], v243 offset:29504
	ds_read_b128 v[200:203], v243 offset:38656
	ds_read_b128 v[176:179], v243 offset:38720
	v_mul_f32_e32 v3, v53, v53
	v_fmac_f32_e32 v3, v52, v52
	v_fmac_f32_e32 v3, v54, v54
	v_fmac_f32_e32 v3, v55, v55
	s_waitcnt lgkmcnt(7)
	v_mfma_f32_16x16x32_bf16 v[82:85], v[78:81], v[222:225], 0
	s_waitcnt lgkmcnt(6)
	v_mfma_f32_16x16x32_bf16 v[82:85], v[56:59], v[226:229], v[82:85]
	s_waitcnt lgkmcnt(5)
	v_mfma_f32_16x16x32_bf16 v[82:85], v[78:81], v[230:233], v[82:85]
	s_waitcnt lgkmcnt(4)
	v_mfma_f32_16x16x32_bf16 v[82:85], v[56:59], v[234:237], v[82:85]
	s_waitcnt lgkmcnt(3)
	v_mfma_f32_16x16x32_bf16 v[8:11], v[8:11], v[238:241], v[82:85]
	s_waitcnt lgkmcnt(2)
	v_mfma_f32_16x16x32_bf16 v[8:11], v[12:15], v[196:199], v[8:11]
	s_waitcnt lgkmcnt(1)
	v_mfma_f32_16x16x32_bf16 v[8:11], v[16:19], v[200:203], v[8:11]
	s_waitcnt lgkmcnt(0)
	v_mfma_f32_16x16x32_bf16 v[8:11], v[20:23], v[176:179], v[8:11]
	v_mul_f32_e32 v13, v49, v49
	v_mul_f32_e32 v15, v45, v45
	v_fmac_f32_e32 v13, v48, v48
	s_nop 4
	v_mul_f32_e32 v17, v9, v9
	v_fmac_f32_e32 v15, v44, v44
	v_fmac_f32_e32 v17, v8, v8
	v_fmac_f32_e32 v13, v50, v50
	v_fmac_f32_e32 v15, v46, v46
	v_fmac_f32_e32 v17, v10, v10
	v_fmac_f32_e32 v13, v51, v51
	v_fmac_f32_e32 v15, v47, v47
	v_fmac_f32_e32 v17, v11, v11
	ds_bpermute_b32 v12, v209, v3
	ds_bpermute_b32 v14, v209, v13
	ds_bpermute_b32 v16, v209, v15
	ds_bpermute_b32 v18, v209, v17
	s_waitcnt lgkmcnt(0)
	v_add_f32_e32 v3, v3, v12
	v_add_f32_e32 v13, v13, v14
	v_add_f32_e32 v15, v15, v16
	v_add_f32_e32 v17, v17, v18
	ds_bpermute_b32 v12, v215, v3
	ds_bpermute_b32 v14, v215, v13
	ds_bpermute_b32 v16, v215, v15
	ds_bpermute_b32 v18, v215, v17
	s_and_saveexec_b64 s[6:7], vcc
	s_cbranch_execz .LBB0_177
	s_and_b32 s9, s27, 0x3fffffc0
	s_lshl_b32 s9, s9, 2
	s_add_i32 s9, s9, 0
	s_waitcnt lgkmcnt(0)
	v_add_f32_e32 v3, v3, v12
	v_lshl_add_u32 v12, v123, 2, s9
	v_add_f32_e32 v13, v13, v14
	v_add_u32_e32 v12, 0x5000, v12
	v_add_f32_e32 v17, v17, v18
	v_add_f32_e32 v15, v15, v16
	ds_write2_b32 v12, v3, v13 offset1:16
	ds_write2_b32 v12, v15, v17 offset0:32 offset1:48
	s_branch .LBB0_177
